# back-edge rotation of the FFN-up GEMM K loop: counter/pointer updates and next-iteration scalar set-up moved above the loop-back barrier
# baseline (speedup 1.0000x reference)
; #define PG8_STAGE(bufoff, gbase, voff) do { _Pragma("unroll") for (int _i = 0; _i < 2; ++_i) \
;         __builtin_amdgcn_global_load_lds((const unsigned*)((const char*)(gbase) + (voff)[_i]), (PG8_LAS unsigned*)(lds + (bufoff) + ldsw + _i * 8192), 16, 0, 0); } while (0)
; #define PG8_LDA(dst, b, h) do { _Pragma("unroll") for (int m = 0; m < 4; ++m) _Pragma("unroll") for (int k = 0; k < 2; ++k) dst[m][k] = *(const PG8_LAS bf16x8*)(lds + PG8_SA(b, h) + aoff + m * 2048 + k * 1024); } while (0)
; #define PG8_LDB(dst, b, h) do { _Pragma("unroll") for (int n = 0; n < 2; ++n) _Pragma("unroll") for (int k = 0; k < 2; ++k) dst[n][k] = *(const PG8_LAS bf16x8*)(lds + PG8_SB(b, h) + boff + n * 2048 + k * 1024); } while (0)
; #define PG8_MMA(ai, bj, At, Bt) do { __builtin_amdgcn_s_setprio(1); _Pragma("unroll") for (int m = 0; m < 4; ++m) _Pragma("unroll") for (int n = 0; n < 2; ++n) _Pragma("unroll") for (int k = 0; k < 2; ++k) \
;         acc[ai][bj][m][n] = __builtin_amdgcn_mfma_f32_16x16x32_bf16(Bt[n][k], At[m][k], acc[ai][bj][m][n], 0, 0, 0); __builtin_amdgcn_s_setprio(0); } while (0)
; #define PG8_WAIT_V(n) asm volatile("s_waitcnt vmcnt(" #n ")" ::: "memory")
; #define PG8_WAIT_L(n) asm volatile("s_waitcnt lgkmcnt(" #n ")" ::: "memory")
; #define PG8_BAR __builtin_amdgcn_s_barrier()
; #define PG8_SCHED __builtin_amdgcn_sched_barrier(0)
; template <class Epi, class Sched, bool ALIGN_EPI = false, bool SP2 = false>
; __device__ __forceinline__ void gemm_phase(PG8_LAS unsigned char* lds, const Gemm g, const Sched& S, const Epi& E) {
;     ...
;         for (int t = 0; t < nt; t += 2) {
;             const bool last = (t == nt - 2);
;             const char* a1 = cA + (size_t)(t + 1) * kstep;
;             const char* a2 = last ? nA : cA + (size_t)(t + 2) * kstep; const char* b2 = last ? nB : cB + (size_t)(t + 2) * kstep;
;             const char* a3 = a2 + kstep; const char* b3 = b2 + kstep;
;             if (last && has_next) S.a_ready(nxt);
;             if constexpr (SP2) {
;             PG8_LDB(B0, 0, 0); PG8_LDB(B1, 0, 1); PG8_SCHED; PG8_LDA(At, 0, 0); PG8_STAGE(PG8_SA(1, 1), a1 + hstep, voffA);
;             PG8_WAIT_V(8); PG8_WAIT_L(0); PG8_BAR; PG8_MMA(0, 0, At, B0); PG8_MMA(0, 1, At, B1); PG8_BAR; PG8_SCHED;
.LBB0_352:
	s_ashr_i32 s13, s12, 31
	s_lshl_b64 s[14:15], s[12:13], 20
	s_add_u32 s14, s28, s14
	s_addc_u32 s15, s29, s15
	s_and_b64 s[16:17], s[6:7], exec
	s_cselect_b32 s13, s15, s21
	s_cselect_b32 s47, s14, s20
	s_ashr_i32 s11, s10, 31
	s_lshl_b64 s[16:17], s[10:11], 20
	s_add_u32 s16, s30, s16
	s_addc_u32 s17, s31, s17
	s_and_b64 s[24:25], s[6:7], exec
	s_cselect_b32 s11, s17, s23
	s_cselect_b32 s48, s16, s22
	s_add_u32 s20, s20, 0x80080
	s_addc_u32 s21, s21, 0
	s_add_u32 s49, s22, 0x100
	v_mov_b32_e32 v4, 0
	s_addc_u32 s50, s23, 0
	s_mov_b32 s51, -2
	v_mov_b64_e32 v[4:5], 0
	v_mov_b64_e32 v[6:7], 0
	v_mov_b64_e32 v[8:9], 0
	v_mov_b64_e32 v[10:11], 0
	v_mov_b64_e32 v[12:13], 0
	v_mov_b64_e32 v[14:15], 0
	v_mov_b64_e32 v[16:17], 0
	v_mov_b64_e32 v[18:19], 0
	v_mov_b64_e32 v[20:21], 0
	v_mov_b64_e32 v[22:23], 0
	v_mov_b64_e32 v[24:25], 0
	v_mov_b64_e32 v[26:27], 0
	v_mov_b64_e32 v[28:29], 0
	v_mov_b64_e32 v[30:31], 0
	v_mov_b64_e32 v[32:33], 0
	v_mov_b64_e32 v[34:35], 0
	v_mov_b64_e32 v[36:37], 0
	v_mov_b64_e32 v[38:39], 0
	v_mov_b64_e32 v[40:41], 0
	v_mov_b64_e32 v[42:43], 0
	v_mov_b64_e32 v[44:45], 0
	v_mov_b64_e32 v[46:47], 0
	v_mov_b64_e32 v[48:49], 0
	v_mov_b64_e32 v[50:51], 0
	v_mov_b64_e32 v[52:53], 0
	v_mov_b64_e32 v[54:55], 0
	v_mov_b64_e32 v[56:57], 0
	v_mov_b64_e32 v[58:59], 0
	v_mov_b64_e32 v[60:61], 0
	v_mov_b64_e32 v[62:63], 0
	v_mov_b64_e32 v[64:65], 0
	v_mov_b64_e32 v[66:67], 0
	v_mov_b64_e32 v[68:69], 0
	v_mov_b64_e32 v[70:71], 0
	v_mov_b64_e32 v[72:73], 0
	v_mov_b64_e32 v[74:75], 0
	v_mov_b64_e32 v[76:77], 0
	v_mov_b64_e32 v[78:79], 0
	v_mov_b64_e32 v[80:81], 0
	v_mov_b64_e32 v[82:83], 0
	v_mov_b64_e32 v[84:85], 0
	v_mov_b64_e32 v[86:87], 0
	v_mov_b64_e32 v[88:89], 0
	v_mov_b64_e32 v[90:91], 0
	v_mov_b64_e32 v[92:93], 0
	v_mov_b64_e32 v[94:95], 0
	v_mov_b64_e32 v[96:97], 0
	v_mov_b64_e32 v[98:99], 0
	v_mov_b64_e32 v[100:101], 0
	v_mov_b64_e32 v[102:103], 0
	v_mov_b64_e32 v[104:105], 0
	v_mov_b64_e32 v[106:107], 0
	v_mov_b64_e32 v[108:109], 0
	v_mov_b64_e32 v[110:111], 0
	v_mov_b64_e32 v[112:113], 0
	v_mov_b64_e32 v[114:115], 0
	v_mov_b64_e32 v[116:117], 0
	v_mov_b64_e32 v[118:119], 0
	v_mov_b64_e32 v[120:121], 0
	v_mov_b64_e32 v[122:123], 0
	v_mov_b64_e32 v[124:125], 0
	v_mov_b64_e32 v[126:127], 0
	v_mov_b64_e32 v[128:129], 0
	v_mov_b64_e32 v[130:131], 0
	s_add_u32 s22, s20, 0xfff80080
	s_addc_u32 s23, s21, -1
	s_cmp_eq_u32 s51, 28
	s_cselect_b32 s25, s13, s23
	s_cselect_b32 s24, s47, s22
	v_add_u32_e32 v144, s74, v135
	s_cselect_b32 s23, s11, s50
	s_cselect_b32 s22, s48, s49
	s_add_i32 s54, 0, 0x14000
.LBB0_353:
	ds_read_b128 v[148:151], v144
	ds_read_b128 v[152:155], v144 offset:1024
	ds_read_b128 v[156:159], v144 offset:2048
	ds_read_b128 v[160:163], v144 offset:3072
	v_add_u32_e32 v144, s54, v135
	ds_read_b128 v[164:167], v144
	ds_read_b128 v[198:201], v144 offset:1024
	ds_read_b128 v[202:205], v144 offset:2048
	ds_read_b128 v[206:209], v144 offset:3072
	v_lshl_add_u64 v[144:145], s[20:21], 0, v[140:141]
	s_add_i32 m0, s38, 0xc000
	ds_read_b128 v[210:213], v147
	ds_read_b128 v[214:217], v147 offset:1024
	ds_read_b128 v[218:221], v147 offset:2048
	ds_read_b128 v[222:225], v147 offset:3072
	ds_read_b128 v[226:229], v147 offset:4096
	ds_read_b128 v[230:233], v147 offset:5120
	ds_read_b128 v[234:237], v147 offset:6144
	ds_read_b128 v[238:241], v147 offset:7168
	global_load_lds_dwordx4 v[144:145], off
	v_lshl_add_u64 v[144:145], s[20:21], 0, v[142:143]
	s_add_i32 m0, s38, 0xe000
	s_nop 0
	global_load_lds_dwordx4 v[144:145], off
	s_waitcnt vmcnt(8)
	s_waitcnt lgkmcnt(0)
	s_barrier
	s_setprio 1
	s_waitcnt lgkmcnt(0)
	v_mfma_f32_16x16x32_bf16 v[128:131], v[148:151], v[210:213], v[128:131]
	v_mfma_f32_16x16x32_bf16 v[120:123], v[156:159], v[210:213], v[120:123]
	v_mfma_f32_16x16x32_bf16 v[112:115], v[148:151], v[218:221], v[112:115]
	v_mfma_f32_16x16x32_bf16 v[104:107], v[156:159], v[218:221], v[104:107]
	v_mfma_f32_16x16x32_bf16 v[96:99], v[148:151], v[226:229], v[96:99]
	v_mfma_f32_16x16x32_bf16 v[88:91], v[156:159], v[226:229], v[88:91]
	v_mfma_f32_16x16x32_bf16 v[80:83], v[148:151], v[234:237], v[80:83]
	v_mfma_f32_16x16x32_bf16 v[72:75], v[156:159], v[234:237], v[72:75]
	v_mfma_f32_16x16x32_bf16 v[128:131], v[152:155], v[214:217], v[128:131]
	v_mfma_f32_16x16x32_bf16 v[120:123], v[160:163], v[214:217], v[120:123]
	v_mfma_f32_16x16x32_bf16 v[112:115], v[152:155], v[222:225], v[112:115]
	v_mfma_f32_16x16x32_bf16 v[104:107], v[160:163], v[222:225], v[104:107]
	v_mfma_f32_16x16x32_bf16 v[96:99], v[152:155], v[230:233], v[96:99]
	v_mfma_f32_16x16x32_bf16 v[88:91], v[160:163], v[230:233], v[88:91]
	v_mfma_f32_16x16x32_bf16 v[80:83], v[152:155], v[238:241], v[80:83]
	v_mfma_f32_16x16x32_bf16 v[72:75], v[160:163], v[238:241], v[72:75]
	s_setprio 0
	s_setprio 1
	v_mfma_f32_16x16x32_bf16 v[124:127], v[164:167], v[210:213], v[124:127]
	v_mfma_f32_16x16x32_bf16 v[116:119], v[202:205], v[210:213], v[116:119]
	v_mfma_f32_16x16x32_bf16 v[108:111], v[164:167], v[218:221], v[108:111]
	v_mfma_f32_16x16x32_bf16 v[100:103], v[202:205], v[218:221], v[100:103]
	v_mfma_f32_16x16x32_bf16 v[92:95], v[164:167], v[226:229], v[92:95]
	v_mfma_f32_16x16x32_bf16 v[84:87], v[202:205], v[226:229], v[84:87]
	v_mfma_f32_16x16x32_bf16 v[76:79], v[164:167], v[234:237], v[76:79]
	v_mfma_f32_16x16x32_bf16 v[68:71], v[202:205], v[234:237], v[68:71]
	v_mfma_f32_16x16x32_bf16 v[124:127], v[198:201], v[214:217], v[124:127]
	v_mfma_f32_16x16x32_bf16 v[116:119], v[206:209], v[214:217], v[116:119]
	v_mfma_f32_16x16x32_bf16 v[108:111], v[198:201], v[222:225], v[108:111]
	v_mfma_f32_16x16x32_bf16 v[100:103], v[206:209], v[222:225], v[100:103]
	v_mfma_f32_16x16x32_bf16 v[92:95], v[198:201], v[230:233], v[92:95]
	v_mfma_f32_16x16x32_bf16 v[84:87], v[206:209], v[230:233], v[84:87]
	v_mfma_f32_16x16x32_bf16 v[76:79], v[198:201], v[238:241], v[76:79]
	v_mfma_f32_16x16x32_bf16 v[68:71], v[206:209], v[238:241], v[68:71]
	s_setprio 0
	s_barrier
; #define PG8_STAGE(bufoff, gbase, voff) do { _Pragma("unroll") for (int _i = 0; _i < 2; ++_i) \
;         __builtin_amdgcn_global_load_lds((const unsigned*)((const char*)(gbase) + (voff)[_i]), (PG8_LAS unsigned*)(lds + (bufoff) + ldsw + _i * 8192), 16, 0, 0); } while (0)
; #define PG8_LDA(dst, b, h) do { _Pragma("unroll") for (int m = 0; m < 4; ++m) _Pragma("unroll") for (int k = 0; k < 2; ++k) dst[m][k] = *(const PG8_LAS bf16x8*)(lds + PG8_SA(b, h) + aoff + m * 2048 + k * 1024); } while (0)
; #define PG8_LDB(dst, b, h) do { _Pragma("unroll") for (int n = 0; n < 2; ++n) _Pragma("unroll") for (int k = 0; k < 2; ++k) dst[n][k] = *(const PG8_LAS bf16x8*)(lds + PG8_SB(b, h) + boff + n * 2048 + k * 1024); } while (0)
; #define PG8_MMA(ai, bj, At, Bt) do { __builtin_amdgcn_s_setprio(1); _Pragma("unroll") for (int m = 0; m < 4; ++m) _Pragma("unroll") for (int n = 0; n < 2; ++n) _Pragma("unroll") for (int k = 0; k < 2; ++k) \
;         acc[ai][bj][m][n] = __builtin_amdgcn_mfma_f32_16x16x32_bf16(Bt[n][k], At[m][k], acc[ai][bj][m][n], 0, 0, 0); __builtin_amdgcn_s_setprio(0); } while (0)
; #define PG8_WAIT_V(n) asm volatile("s_waitcnt vmcnt(" #n ")" ::: "memory")
; #define PG8_WAIT_L(n) asm volatile("s_waitcnt lgkmcnt(" #n ")" ::: "memory")
; #define PG8_BAR __builtin_amdgcn_s_barrier()
; #define PG8_SCHED __builtin_amdgcn_sched_barrier(0)
; template <class Epi, class Sched, bool ALIGN_EPI = false, bool SP2 = false>
; __device__ __forceinline__ void gemm_phase(PG8_LAS unsigned char* lds, const Gemm g, const Sched& S, const Epi& E) {
;     ...
;             PG8_LDA(At, 0, 1); PG8_STAGE(PG8_SB(0, 0), b2, voffB); PG8_STAGE(PG8_SB(0, 1), b2 + hstep, voffB); PG8_STAGE(PG8_SA(0, 0), a2, voffA);
;             PG8_WAIT_V(8); PG8_WAIT_L(0); PG8_BAR; PG8_MMA(1, 0, At, B0); PG8_MMA(1, 1, At, B1); PG8_BAR; PG8_SCHED;
;             PG8_LDB(B0, 1, 0); PG8_LDB(B1, 1, 1); PG8_SCHED; PG8_LDA(At, 1, 0); PG8_STAGE(PG8_SA(0, 1), a2 + hstep, voffA);
	s_add_i32 s52, s74, s34
	v_lshl_add_u64 v[144:145], s[22:23], 0, v[2:3]
	s_mov_b32 m0, s52
	ds_read_b128 v[210:213], v147 offset:16384
	ds_read_b128 v[214:217], v147 offset:17408
	ds_read_b128 v[218:221], v147 offset:18432
	ds_read_b128 v[222:225], v147 offset:19456
	ds_read_b128 v[226:229], v147 offset:20480
	ds_read_b128 v[230:233], v147 offset:21504
	ds_read_b128 v[234:237], v147 offset:22528
	ds_read_b128 v[238:241], v147 offset:23552
	global_load_lds_dwordx4 v[144:145], off
	s_add_i32 m0, s52, 0x2000
	s_add_u32 s52, s22, 0x80000
	v_lshl_add_u64 v[242:243], s[22:23], 0, v[0:1]
	s_addc_u32 s53, s23, 0
	s_add_i32 s54, s54, s34
	global_load_lds_dwordx4 v[242:243], off
	v_lshl_add_u64 v[248:249], s[52:53], 0, v[2:3]
	s_mov_b32 m0, s54
	v_lshl_add_u64 v[250:251], s[24:25], 0, v[136:137]
	global_load_lds_dwordx4 v[248:249], off
	v_lshl_add_u64 v[248:249], s[52:53], 0, v[0:1]
	s_add_i32 m0, s54, 0x2000
	s_nop 0
	global_load_lds_dwordx4 v[248:249], off
	v_lshl_add_u64 v[248:249], s[24:25], 0, v[138:139]
	s_mov_b32 m0, s38
	s_nop 0
	global_load_lds_dwordx4 v[248:249], off
	s_mov_b32 m0, s39
	s_nop 0
	global_load_lds_dwordx4 v[250:251], off
	s_waitcnt vmcnt(8)
	s_waitcnt lgkmcnt(0)
	s_barrier
	s_setprio 1
	s_waitcnt lgkmcnt(0)
	v_mfma_f32_16x16x32_bf16 v[64:67], v[148:151], v[210:213], v[64:67]
	v_mfma_f32_16x16x32_bf16 v[56:59], v[156:159], v[210:213], v[56:59]
	v_mfma_f32_16x16x32_bf16 v[48:51], v[148:151], v[218:221], v[48:51]
	v_mfma_f32_16x16x32_bf16 v[40:43], v[156:159], v[218:221], v[40:43]
	v_mfma_f32_16x16x32_bf16 v[32:35], v[148:151], v[226:229], v[32:35]
	v_mfma_f32_16x16x32_bf16 v[24:27], v[156:159], v[226:229], v[24:27]
	v_mfma_f32_16x16x32_bf16 v[16:19], v[148:151], v[234:237], v[16:19]
	v_mfma_f32_16x16x32_bf16 v[8:11], v[156:159], v[234:237], v[8:11]
	v_mfma_f32_16x16x32_bf16 v[64:67], v[152:155], v[214:217], v[64:67]
	v_mfma_f32_16x16x32_bf16 v[56:59], v[160:163], v[214:217], v[56:59]
	v_mfma_f32_16x16x32_bf16 v[48:51], v[152:155], v[222:225], v[48:51]
	v_mfma_f32_16x16x32_bf16 v[40:43], v[160:163], v[222:225], v[40:43]
	v_mfma_f32_16x16x32_bf16 v[32:35], v[152:155], v[230:233], v[32:35]
	v_mfma_f32_16x16x32_bf16 v[24:27], v[160:163], v[230:233], v[24:27]
	v_mfma_f32_16x16x32_bf16 v[16:19], v[152:155], v[238:241], v[16:19]
	v_mfma_f32_16x16x32_bf16 v[8:11], v[160:163], v[238:241], v[8:11]
	s_setprio 0
	s_setprio 1
	v_mfma_f32_16x16x32_bf16 v[60:63], v[164:167], v[210:213], v[60:63]
	v_mfma_f32_16x16x32_bf16 v[52:55], v[202:205], v[210:213], v[52:55]
	v_mfma_f32_16x16x32_bf16 v[44:47], v[164:167], v[218:221], v[44:47]
	v_mfma_f32_16x16x32_bf16 v[36:39], v[202:205], v[218:221], v[36:39]
	v_mfma_f32_16x16x32_bf16 v[28:31], v[164:167], v[226:229], v[28:31]
	v_mfma_f32_16x16x32_bf16 v[20:23], v[202:205], v[226:229], v[20:23]
	v_mfma_f32_16x16x32_bf16 v[12:15], v[164:167], v[234:237], v[12:15]
	v_mfma_f32_16x16x32_bf16 v[4:7], v[202:205], v[234:237], v[4:7]
	v_mfma_f32_16x16x32_bf16 v[60:63], v[198:201], v[214:217], v[60:63]
	v_mfma_f32_16x16x32_bf16 v[52:55], v[206:209], v[214:217], v[52:55]
	v_mfma_f32_16x16x32_bf16 v[44:47], v[198:201], v[222:225], v[44:47]
	v_mfma_f32_16x16x32_bf16 v[36:39], v[206:209], v[222:225], v[36:39]
	v_mfma_f32_16x16x32_bf16 v[28:31], v[198:201], v[230:233], v[28:31]
	v_mfma_f32_16x16x32_bf16 v[20:23], v[206:209], v[230:233], v[20:23]
	v_mfma_f32_16x16x32_bf16 v[12:15], v[198:201], v[238:241], v[12:15]
	v_mfma_f32_16x16x32_bf16 v[4:7], v[206:209], v[238:241], v[4:7]
	s_setprio 0
	s_barrier
	s_add_i32 s52, 0, 0x18000
	s_add_i32 s53, 0, 0x1c000
	v_add_u32_e32 v160, s52, v135
	v_add_u32_e32 v194, s53, v135
	ds_read_b128 v[148:151], v160
	ds_read_b128 v[152:155], v160 offset:1024
	ds_read_b128 v[156:159], v160 offset:2048
	ds_read_b128 v[160:163], v160 offset:3072
	ds_read_b128 v[164:167], v194
	ds_read_b128 v[198:201], v194 offset:1024
	ds_read_b128 v[202:205], v194 offset:2048
	ds_read_b128 v[206:209], v194 offset:3072
	s_add_u32 s24, s24, 0x80000
	s_addc_u32 s25, s25, 0
	s_mov_b32 m0, s40
	v_lshl_add_u64 v[252:253], s[24:25], 0, v[138:139]
	ds_read_b128 v[210:213], v147 offset:32768
	ds_read_b128 v[214:217], v147 offset:33792
	ds_read_b128 v[218:221], v147 offset:34816
	ds_read_b128 v[222:225], v147 offset:35840
	ds_read_b128 v[226:229], v147 offset:36864
	ds_read_b128 v[230:233], v147 offset:37888
	ds_read_b128 v[234:237], v147 offset:38912
	ds_read_b128 v[238:241], v147 offset:39936
	global_load_lds_dwordx4 v[252:253], off
	v_lshl_add_u64 v[252:253], s[24:25], 0, v[136:137]
	s_mov_b32 m0, s41
	s_nop 0
	global_load_lds_dwordx4 v[252:253], off
	s_waitcnt vmcnt(8)
	s_waitcnt lgkmcnt(0)
	s_barrier
; #define PG8_STAGE(bufoff, gbase, voff) do { _Pragma("unroll") for (int _i = 0; _i < 2; ++_i) \
;         __builtin_amdgcn_global_load_lds((const unsigned*)((const char*)(gbase) + (voff)[_i]), (PG8_LAS unsigned*)(lds + (bufoff) + ldsw + _i * 8192), 16, 0, 0); } while (0)
; #define PG8_LDA(dst, b, h) do { _Pragma("unroll") for (int m = 0; m < 4; ++m) _Pragma("unroll") for (int k = 0; k < 2; ++k) dst[m][k] = *(const PG8_LAS bf16x8*)(lds + PG8_SA(b, h) + aoff + m * 2048 + k * 1024); } while (0)
; #define PG8_LDB(dst, b, h) do { _Pragma("unroll") for (int n = 0; n < 2; ++n) _Pragma("unroll") for (int k = 0; k < 2; ++k) dst[n][k] = *(const PG8_LAS bf16x8*)(lds + PG8_SB(b, h) + boff + n * 2048 + k * 1024); } while (0)
; #define PG8_MMA(ai, bj, At, Bt) do { __builtin_amdgcn_s_setprio(1); _Pragma("unroll") for (int m = 0; m < 4; ++m) _Pragma("unroll") for (int n = 0; n < 2; ++n) _Pragma("unroll") for (int k = 0; k < 2; ++k) \
;         acc[ai][bj][m][n] = __builtin_amdgcn_mfma_f32_16x16x32_bf16(Bt[n][k], At[m][k], acc[ai][bj][m][n], 0, 0, 0); __builtin_amdgcn_s_setprio(0); } while (0)
; #define PG8_WAIT_V(n) asm volatile("s_waitcnt vmcnt(" #n ")" ::: "memory")
; #define PG8_WAIT_L(n) asm volatile("s_waitcnt lgkmcnt(" #n ")" ::: "memory")
; #define PG8_BAR __builtin_amdgcn_s_barrier()
; template <class Epi, class Sched, bool ALIGN_EPI = false, bool SP2 = false>
; __device__ __forceinline__ void gemm_phase(PG8_LAS unsigned char* lds, const Gemm g, const Sched& S, const Epi& E) {
;     ...
;         for (int t = 0; t < nt; t += 2) {
;             const bool last = (t == nt - 2);
;             const char* a1 = cA + (size_t)(t + 1) * kstep;
;             const char* a2 = last ? nA : cA + (size_t)(t + 2) * kstep; const char* b2 = last ? nB : cB + (size_t)(t + 2) * kstep;
;             const char* a3 = a2 + kstep; const char* b3 = b2 + kstep;
;     ...
;             PG8_LDB(B0, 1, 0); PG8_LDB(B1, 1, 1); PG8_SCHED; PG8_LDA(At, 1, 0); PG8_STAGE(PG8_SA(0, 1), a2 + hstep, voffA);
;             PG8_WAIT_V(8); PG8_WAIT_L(0); PG8_BAR; PG8_MMA(0, 0, At, B0); PG8_MMA(0, 1, At, B1); PG8_BAR; PG8_SCHED;
;             PG8_LDA(At, 1, 1); PG8_STAGE(PG8_SB(1, 0), b3, voffB); PG8_STAGE(PG8_SB(1, 1), b3 + hstep, voffB); PG8_STAGE(PG8_SA(1, 0), a3, voffA);
;             PG8_WAIT_V(8); PG8_WAIT_L(0); PG8_BAR; PG8_MMA(1, 0, At, B0); PG8_MMA(1, 1, At, B1); PG8_BAR; PG8_SCHED;
	s_setprio 1
	s_waitcnt lgkmcnt(0)
	v_mfma_f32_16x16x32_bf16 v[128:131], v[148:151], v[210:213], v[128:131]
	v_mfma_f32_16x16x32_bf16 v[120:123], v[156:159], v[210:213], v[120:123]
	v_mfma_f32_16x16x32_bf16 v[112:115], v[148:151], v[218:221], v[112:115]
	v_mfma_f32_16x16x32_bf16 v[104:107], v[156:159], v[218:221], v[104:107]
	v_mfma_f32_16x16x32_bf16 v[96:99], v[148:151], v[226:229], v[96:99]
	v_mfma_f32_16x16x32_bf16 v[88:91], v[156:159], v[226:229], v[88:91]
	v_mfma_f32_16x16x32_bf16 v[80:83], v[148:151], v[234:237], v[80:83]
	v_mfma_f32_16x16x32_bf16 v[72:75], v[156:159], v[234:237], v[72:75]
	v_mfma_f32_16x16x32_bf16 v[128:131], v[152:155], v[214:217], v[128:131]
	v_mfma_f32_16x16x32_bf16 v[120:123], v[160:163], v[214:217], v[120:123]
	v_mfma_f32_16x16x32_bf16 v[112:115], v[152:155], v[222:225], v[112:115]
	v_mfma_f32_16x16x32_bf16 v[104:107], v[160:163], v[222:225], v[104:107]
	v_mfma_f32_16x16x32_bf16 v[96:99], v[152:155], v[230:233], v[96:99]
	v_mfma_f32_16x16x32_bf16 v[88:91], v[160:163], v[230:233], v[88:91]
	v_mfma_f32_16x16x32_bf16 v[80:83], v[152:155], v[238:241], v[80:83]
	v_mfma_f32_16x16x32_bf16 v[72:75], v[160:163], v[238:241], v[72:75]
	s_setprio 0
	s_setprio 1
	v_mfma_f32_16x16x32_bf16 v[124:127], v[164:167], v[210:213], v[124:127]
	v_mfma_f32_16x16x32_bf16 v[116:119], v[202:205], v[210:213], v[116:119]
	v_mfma_f32_16x16x32_bf16 v[108:111], v[164:167], v[218:221], v[108:111]
	v_mfma_f32_16x16x32_bf16 v[100:103], v[202:205], v[218:221], v[100:103]
	v_mfma_f32_16x16x32_bf16 v[92:95], v[164:167], v[226:229], v[92:95]
	v_mfma_f32_16x16x32_bf16 v[84:87], v[202:205], v[226:229], v[84:87]
	v_mfma_f32_16x16x32_bf16 v[76:79], v[164:167], v[234:237], v[76:79]
	v_mfma_f32_16x16x32_bf16 v[68:71], v[202:205], v[234:237], v[68:71]
	v_mfma_f32_16x16x32_bf16 v[124:127], v[198:201], v[214:217], v[124:127]
	v_mfma_f32_16x16x32_bf16 v[116:119], v[206:209], v[214:217], v[116:119]
	v_mfma_f32_16x16x32_bf16 v[108:111], v[198:201], v[222:225], v[108:111]
	v_mfma_f32_16x16x32_bf16 v[100:103], v[206:209], v[222:225], v[100:103]
	v_mfma_f32_16x16x32_bf16 v[92:95], v[198:201], v[230:233], v[92:95]
	v_mfma_f32_16x16x32_bf16 v[84:87], v[206:209], v[230:233], v[84:87]
	v_mfma_f32_16x16x32_bf16 v[76:79], v[198:201], v[238:241], v[76:79]
	v_mfma_f32_16x16x32_bf16 v[68:71], v[206:209], v[238:241], v[68:71]
	s_setprio 0
	s_barrier
	s_add_i32 s24, s52, s34
	v_lshl_add_u64 v[144:145], v[144:145], 0, s[84:85]
	s_mov_b32 m0, s24
	ds_read_b128 v[210:213], v147 offset:49152
	ds_read_b128 v[214:217], v147 offset:50176
	ds_read_b128 v[218:221], v147 offset:51200
	ds_read_b128 v[222:225], v147 offset:52224
	ds_read_b128 v[226:229], v147 offset:53248
	ds_read_b128 v[230:233], v147 offset:54272
	ds_read_b128 v[234:237], v147 offset:55296
	ds_read_b128 v[238:241], v147 offset:56320
	global_load_lds_dwordx4 v[144:145], off
	s_add_i32 m0, s24, 0x2000
	s_add_u32 s22, s22, 0x80080
	v_lshl_add_u64 v[144:145], v[242:243], 0, s[84:85]
	s_addc_u32 s23, s23, 0
	s_add_i32 s24, s53, s34
	global_load_lds_dwordx4 v[144:145], off
	v_lshl_add_u64 v[144:145], s[22:23], 0, v[2:3]
	s_mov_b32 m0, s24
	s_nop 0
	global_load_lds_dwordx4 v[144:145], off
	v_lshl_add_u64 v[144:145], s[22:23], 0, v[0:1]
	s_add_i32 m0, s24, 0x2000
	s_nop 0
	global_load_lds_dwordx4 v[144:145], off
	v_lshl_add_u64 v[144:145], v[248:249], 0, s[84:85]
	s_mov_b32 m0, s43
	s_nop 0
	global_load_lds_dwordx4 v[144:145], off
	v_lshl_add_u64 v[144:145], v[250:251], 0, s[84:85]
	s_mov_b32 m0, s44
	s_nop 0
	global_load_lds_dwordx4 v[144:145], off
	s_waitcnt vmcnt(8)
	s_waitcnt lgkmcnt(0)
	s_barrier
	s_setprio 1
	s_waitcnt lgkmcnt(0)
	v_mfma_f32_16x16x32_bf16 v[64:67], v[148:151], v[210:213], v[64:67]
	v_mfma_f32_16x16x32_bf16 v[56:59], v[156:159], v[210:213], v[56:59]
	v_mfma_f32_16x16x32_bf16 v[48:51], v[148:151], v[218:221], v[48:51]
	v_mfma_f32_16x16x32_bf16 v[40:43], v[156:159], v[218:221], v[40:43]
	v_mfma_f32_16x16x32_bf16 v[32:35], v[148:151], v[226:229], v[32:35]
	v_mfma_f32_16x16x32_bf16 v[24:27], v[156:159], v[226:229], v[24:27]
	v_mfma_f32_16x16x32_bf16 v[16:19], v[148:151], v[234:237], v[16:19]
	v_mfma_f32_16x16x32_bf16 v[8:11], v[156:159], v[234:237], v[8:11]
	v_mfma_f32_16x16x32_bf16 v[64:67], v[152:155], v[214:217], v[64:67]
	v_mfma_f32_16x16x32_bf16 v[56:59], v[160:163], v[214:217], v[56:59]
	v_mfma_f32_16x16x32_bf16 v[48:51], v[152:155], v[222:225], v[48:51]
	v_mfma_f32_16x16x32_bf16 v[40:43], v[160:163], v[222:225], v[40:43]
	v_mfma_f32_16x16x32_bf16 v[32:35], v[152:155], v[230:233], v[32:35]
	v_mfma_f32_16x16x32_bf16 v[24:27], v[160:163], v[230:233], v[24:27]
	v_mfma_f32_16x16x32_bf16 v[16:19], v[152:155], v[238:241], v[16:19]
	v_mfma_f32_16x16x32_bf16 v[8:11], v[160:163], v[238:241], v[8:11]
	s_setprio 0
	s_setprio 1
	v_mfma_f32_16x16x32_bf16 v[60:63], v[164:167], v[210:213], v[60:63]
	v_mfma_f32_16x16x32_bf16 v[52:55], v[202:205], v[210:213], v[52:55]
	v_mfma_f32_16x16x32_bf16 v[44:47], v[164:167], v[218:221], v[44:47]
	v_mfma_f32_16x16x32_bf16 v[36:39], v[202:205], v[218:221], v[36:39]
	v_mfma_f32_16x16x32_bf16 v[28:31], v[164:167], v[226:229], v[28:31]
	v_mfma_f32_16x16x32_bf16 v[20:23], v[202:205], v[226:229], v[20:23]
	v_mfma_f32_16x16x32_bf16 v[12:15], v[164:167], v[234:237], v[12:15]
	v_mfma_f32_16x16x32_bf16 v[4:7], v[202:205], v[234:237], v[4:7]
	v_mfma_f32_16x16x32_bf16 v[60:63], v[198:201], v[214:217], v[60:63]
	v_mfma_f32_16x16x32_bf16 v[52:55], v[206:209], v[214:217], v[52:55]
	v_mfma_f32_16x16x32_bf16 v[44:47], v[198:201], v[222:225], v[44:47]
	v_mfma_f32_16x16x32_bf16 v[36:39], v[206:209], v[222:225], v[36:39]
	v_mfma_f32_16x16x32_bf16 v[28:31], v[198:201], v[230:233], v[28:31]
	v_mfma_f32_16x16x32_bf16 v[20:23], v[206:209], v[230:233], v[20:23]
	v_mfma_f32_16x16x32_bf16 v[12:15], v[198:201], v[238:241], v[12:15]
	v_mfma_f32_16x16x32_bf16 v[4:7], v[206:209], v[238:241], v[4:7]
	s_setprio 0
	s_add_i32 s51, s51, 2
	s_add_u32 s20, s20, 0x100
	s_addc_u32 s21, s21, 0
	s_add_u32 s49, s49, 0x100
	s_addc_u32 s50, s50, 0
	s_add_u32 s22, s20, 0xfff80080
	s_addc_u32 s23, s21, -1
	s_cmp_eq_u32 s51, 28
	s_cselect_b32 s25, s13, s23
	s_cselect_b32 s24, s47, s22
	v_add_u32_e32 v144, s74, v135
	s_cselect_b32 s23, s11, s50
	s_cselect_b32 s22, s48, s49
	s_add_i32 s54, 0, 0x14000
	s_cmp_gt_u32 s51, 29
	s_barrier
	s_cbranch_scc0 .LBB0_353
	s_and_b64 vcc, exec, s[8:9]
	s_cbranch_vccz .LBB0_356
	s_barrier
